# v24 plus hand-written attention epilogue: LDS transpose of O, 16-byte gate loads and 16-byte output stores instead of 2-byte accesses
# baseline (speedup 1.0000x reference)
; __device__ __forceinline__ float bf2f(unsigned short b) { return __uint_as_float(((unsigned)b) << 16); }
; __device__ __forceinline__ unsigned short f2bf(float f) { return (unsigned short)(cvtpk(f, f) & 0xffffu); }
; __device__ __forceinline__ float siluf_(float x) { return x * sigmoidf_(x); }
; #define SBAR() __builtin_amdgcn_sched_barrier(0)
; __device__ __forceinline__ int crow(int r, int hi) { return (r & 3) + 8 * (r >> 2) + 4 * hi; }
; __device__ __forceinline__ void attn_body(const bf16_t* __restrict__ Qb, const bf16_t* __restrict__ Kh, const bf16_t* __restrict__ Vh,
;                                           bf16_t* __restrict__ Ob, const bf16_t* __restrict__ AGb, int seq, char* lds) {
;     ...
;   if (hi == 0) li_l[r32] = l_reg; asm volatile("s_waitcnt lgkmcnt(0)" ::: "memory");
;   char* Ow = (char*)(Ob + (long)(wid * QBLK) * LDO); const char* Gw = (const char*)(AGb + (long)(wid * QBLK) * LDQ);
;   unsigned hv = hi, cv = r32;
;   asm volatile("" : "+v"(hv), "+v"(cv));
;   const unsigned gbase = (hv * 4u * LDQ + cv) * 2u, obase = (hv * 4u * LDO + cv) * 2u;
;   unsigned short gq[16][4];
; #pragma unroll
;   for (int r = 0; r < 16; ++r) { const int rc = (r & 3) + 8 * (r >> 2); const unsigned go = gbase + (unsigned)(rc * LDQ * 2);
; #pragma unroll
;     for (int d0 = 0; d0 < 4; ++d0) gq[r][d0] = *(const bf16_t*)(Gw + go + d0 * 64); }
;   SBAR();
; #pragma unroll
;   for (int r = 0; r < 16; ++r) { const int rc = (r & 3) + 8 * (r >> 2); const float rli = __builtin_amdgcn_rcpf(li_l[crow(r, hi)]);
;     const unsigned oo = obase + (unsigned)(rc * LDO * 2);
; #pragma unroll
;     for (int d0 = 0; d0 < 4; ++d0) *(bf16_t*)(Ow + oo + d0 * 64) = f2bf(o[d0][r] * rli * siluf_(bf2f(gq[r][d0]))); }
.LBB0_188:
	s_or_b64 exec, exec, s[0:1]
	s_lshl_b64 s[0:1], s[18:19], 12
	s_add_u32 s0, s47, s0
	s_addc_u32 s1, s66, s1
	s_lshl_b32 s3, s28, 1
	s_add_u32 s0, s0, s3
	s_addc_u32 s1, s1, 0
	s_add_u32 s3, s26, s3
	s_addc_u32 s5, s27, 0
	s_add_u32 s4, s3, 0x1800
	s_mov_b32 s3, 0x11000
	s_addc_u32 s5, s5, 0
	s_waitcnt lgkmcnt(0)
	v_and_b32_e32 v83, 63, v190
	v_lshrrev_b32_e32 v84, 3, v83
	v_and_b32_e32 v85, 7, v83
	v_add_u32_e32 v95, v182, v84
	v_mul_u32_u24_e32 v86, 0x8800, v95
	v_lshl_add_u32 v86, v85, 4, v86
	v_add_u32_e32 v87, 0x44000, v86
	v_add_u32_e32 v88, 0x88000, v86
	v_add_u32_e32 v89, 0xcc000, v86
	global_load_dwordx4 v[100:103], v86, s[4:5]
	global_load_dwordx4 v[104:107], v87, s[4:5]
	global_load_dwordx4 v[108:111], v88, s[4:5]
	global_load_dwordx4 v[112:115], v89, s[4:5]
	global_load_dwordx4 v[116:119], v86, s[4:5] offset:128
	global_load_dwordx4 v[120:123], v87, s[4:5] offset:128
	global_load_dwordx4 v[124:127], v88, s[4:5] offset:128
	global_load_dwordx4 v[128:131], v89, s[4:5] offset:128
	v_lshlrev_b32_e32 v90, 12, v95
	v_lshl_add_u32 v90, v85, 4, v90
	v_add_u32_e32 v91, 0x8000, v90
	v_add_u32_e32 v92, 0x10000, v90
	v_add_u32_e32 v93, 0x18000, v90
	v_add_u32_e32 v94, v181, v180
	ds_read_b128 v[64:67], v94
	ds_read_b128 v[68:71], v94 offset:32
	ds_read_b128 v[72:75], v94 offset:64
	ds_read_b128 v[76:79], v94 offset:96
	v_add_u32_e32 v80, 0xffff0000, v181
	v_lshlrev_b32_e32 v80, 5, v80
	v_bfe_u32 v95, v190, 8, 1
	v_lshl_add_u32 v80, v95, 11, v80
	v_add_u32_e32 v80, 0x8000, v80
	v_lshl_add_u32 v81, v180, 6, v80
	v_lshl_add_u32 v81, v198, 2, v81
	v_lshl_add_u32 v82, v84, 8, v80
	v_lshl_add_u32 v82, v85, 5, v82
	s_waitcnt lgkmcnt(0)
	v_rcp_f32_e32 v64, v64
	v_rcp_f32_e32 v65, v65
	v_rcp_f32_e32 v66, v66
	v_rcp_f32_e32 v67, v67
	v_rcp_f32_e32 v68, v68
	v_rcp_f32_e32 v69, v69
	v_rcp_f32_e32 v70, v70
	v_rcp_f32_e32 v71, v71
	v_rcp_f32_e32 v72, v72
	v_rcp_f32_e32 v73, v73
	v_rcp_f32_e32 v74, v74
	v_rcp_f32_e32 v75, v75
	v_rcp_f32_e32 v76, v76
	v_rcp_f32_e32 v77, v77
	v_rcp_f32_e32 v78, v78
	v_rcp_f32_e32 v79, v79
	v_mul_f32_e32 v0, v0, v64
	v_mul_f32_e32 v1, v1, v65
	v_mul_f32_e32 v2, v2, v66
	v_mul_f32_e32 v3, v3, v67
	v_mul_f32_e32 v4, v4, v68
	v_mul_f32_e32 v5, v5, v69
	v_mul_f32_e32 v6, v6, v70
	v_mul_f32_e32 v7, v7, v71
	v_mul_f32_e32 v8, v8, v72
	v_mul_f32_e32 v9, v9, v73
	v_mul_f32_e32 v10, v10, v74
	v_mul_f32_e32 v11, v11, v75
	v_mul_f32_e32 v12, v12, v76
	v_mul_f32_e32 v13, v13, v77
	v_mul_f32_e32 v14, v14, v78
	v_mul_f32_e32 v15, v15, v79
	v_mul_f32_e32 v48, v48, v64
	v_mul_f32_e32 v49, v49, v65
	v_mul_f32_e32 v50, v50, v66
	v_mul_f32_e32 v51, v51, v67
	v_mul_f32_e32 v52, v52, v68
	v_mul_f32_e32 v53, v53, v69
	v_mul_f32_e32 v54, v54, v70
	v_mul_f32_e32 v55, v55, v71
	v_mul_f32_e32 v56, v56, v72
	v_mul_f32_e32 v57, v57, v73
	v_mul_f32_e32 v58, v58, v74
	v_mul_f32_e32 v59, v59, v75
	v_mul_f32_e32 v60, v60, v76
	v_mul_f32_e32 v61, v61, v77
	v_mul_f32_e32 v62, v62, v78
	v_mul_f32_e32 v63, v63, v79
	v_mul_f32_e32 v32, v32, v64
	v_mul_f32_e32 v33, v33, v65
	v_mul_f32_e32 v34, v34, v66
	v_mul_f32_e32 v35, v35, v67
	v_mul_f32_e32 v36, v36, v68
	v_mul_f32_e32 v37, v37, v69
	v_mul_f32_e32 v38, v38, v70
	v_mul_f32_e32 v39, v39, v71
	v_mul_f32_e32 v40, v40, v72
	v_mul_f32_e32 v41, v41, v73
	v_mul_f32_e32 v42, v42, v74
	v_mul_f32_e32 v43, v43, v75
	v_mul_f32_e32 v44, v44, v76
	v_mul_f32_e32 v45, v45, v77
	v_mul_f32_e32 v46, v46, v78
	v_mul_f32_e32 v47, v47, v79
	v_mul_f32_e32 v16, v16, v64
	v_mul_f32_e32 v17, v17, v65
	v_mul_f32_e32 v18, v18, v66
	v_mul_f32_e32 v19, v19, v67
	v_mul_f32_e32 v20, v20, v68
	v_mul_f32_e32 v21, v21, v69
	v_mul_f32_e32 v22, v22, v70
	v_mul_f32_e32 v23, v23, v71
	v_mul_f32_e32 v24, v24, v72
	v_mul_f32_e32 v25, v25, v73
	v_mul_f32_e32 v26, v26, v74
	v_mul_f32_e32 v27, v27, v75
	v_mul_f32_e32 v28, v28, v76
	v_mul_f32_e32 v29, v29, v77
	v_mul_f32_e32 v30, v30, v78
	v_mul_f32_e32 v31, v31, v79
	ds_write_b32 v81, v0
	ds_write_b32 v81, v1 offset:256
	ds_write_b32 v81, v2 offset:512
	ds_write_b32 v81, v3 offset:768
	ds_write_b32 v81, v4 offset:2048
	ds_write_b32 v81, v5 offset:2304
	ds_write_b32 v81, v6 offset:2560
	ds_write_b32 v81, v7 offset:2816
	ds_write_b32 v81, v8 offset:4096
	ds_write_b32 v81, v9 offset:4352
	ds_write_b32 v81, v10 offset:4608
	ds_write_b32 v81, v11 offset:4864
	ds_write_b32 v81, v12 offset:6144
	ds_write_b32 v81, v13 offset:6400
	ds_write_b32 v81, v14 offset:6656
	ds_write_b32 v81, v15 offset:6912
	ds_write_b32 v81, v48 offset:128
	ds_write_b32 v81, v49 offset:384
	ds_write_b32 v81, v50 offset:640
	ds_write_b32 v81, v51 offset:896
	ds_write_b32 v81, v52 offset:2176
	ds_write_b32 v81, v53 offset:2432
	ds_write_b32 v81, v54 offset:2688
	ds_write_b32 v81, v55 offset:2944
	ds_write_b32 v81, v56 offset:4224
	ds_write_b32 v81, v57 offset:4480
	ds_write_b32 v81, v58 offset:4736
	ds_write_b32 v81, v59 offset:4992
	ds_write_b32 v81, v60 offset:6272
	ds_write_b32 v81, v61 offset:6528
	ds_write_b32 v81, v62 offset:6784
	ds_write_b32 v81, v63 offset:7040
	s_waitcnt lgkmcnt(0)
	ds_read_b128 v[132:135], v82
	ds_read_b128 v[136:139], v82 offset:16
	s_waitcnt vmcnt(0)
	v_lshlrev_b32_e32 v64, 16, v100
	v_and_b32_e32 v65, 0xffff0000, v100
	v_lshlrev_b32_e32 v66, 16, v101
	v_and_b32_e32 v67, 0xffff0000, v101
	v_mul_f32_e32 v68, 0xbfb8aa3b, v64
	v_mul_f32_e32 v69, 0xbfb8aa3b, v65
	v_mul_f32_e32 v70, 0xbfb8aa3b, v66
	v_mul_f32_e32 v71, 0xbfb8aa3b, v67
	v_exp_f32_e32 v68, v68
	v_exp_f32_e32 v69, v69
	v_exp_f32_e32 v70, v70
	v_exp_f32_e32 v71, v71
	s_waitcnt lgkmcnt(0)
; __device__ __forceinline__ float bf2f(unsigned short b) { return __uint_as_float(((unsigned)b) << 16); }
; __device__ __forceinline__ unsigned short f2bf(float f) { return (unsigned short)(cvtpk(f, f) & 0xffffu); }
; __device__ __forceinline__ float siluf_(float x) { return x * sigmoidf_(x); }
; __device__ __forceinline__ int crow(int r, int hi) { return (r & 3) + 8 * (r >> 2) + 4 * hi; }
; __device__ __forceinline__ void attn_body(const bf16_t* __restrict__ Qb, const bf16_t* __restrict__ Kh, const bf16_t* __restrict__ Vh,
;                                           bf16_t* __restrict__ Ob, const bf16_t* __restrict__ AGb, int seq, char* lds) {
;     ...
;   for (int r = 0; r < 16; ++r) { const int rc = (r & 3) + 8 * (r >> 2); const float rli = __builtin_amdgcn_rcpf(li_l[crow(r, hi)]);
;     const unsigned oo = obase + (unsigned)(rc * LDO * 2);
; #pragma unroll
;     for (int d0 = 0; d0 < 4; ++d0) *(bf16_t*)(Ow + oo + d0 * 64) = f2bf(o[d0][r] * rli * siluf_(bf2f(gq[r][d0]))); }
	v_add_f32_e32 v68, 1.0, v68
	v_add_f32_e32 v69, 1.0, v69
	v_add_f32_e32 v70, 1.0, v70
	v_add_f32_e32 v71, 1.0, v71
	v_rcp_f32_e32 v68, v68
	v_rcp_f32_e32 v69, v69
	v_rcp_f32_e32 v70, v70
	v_rcp_f32_e32 v71, v71
	s_nop 0
	v_mul_f32_e32 v64, v68, v64
	v_mul_f32_e32 v65, v69, v65
	v_mul_f32_e32 v66, v70, v66
	v_mul_f32_e32 v67, v71, v67
	v_mul_f32_e32 v132, v64, v132
	v_mul_f32_e32 v133, v65, v133
	v_mul_f32_e32 v134, v66, v134
	v_mul_f32_e32 v135, v67, v135
	v_cvt_pk_bf16_f32 v140, v132, v133
	v_cvt_pk_bf16_f32 v141, v134, v135
	v_lshlrev_b32_e32 v64, 16, v102
	v_and_b32_e32 v65, 0xffff0000, v102
	v_lshlrev_b32_e32 v66, 16, v103
	v_and_b32_e32 v67, 0xffff0000, v103
	v_mul_f32_e32 v68, 0xbfb8aa3b, v64
	v_mul_f32_e32 v69, 0xbfb8aa3b, v65
	v_mul_f32_e32 v70, 0xbfb8aa3b, v66
	v_mul_f32_e32 v71, 0xbfb8aa3b, v67
	v_exp_f32_e32 v68, v68
	v_exp_f32_e32 v69, v69
	v_exp_f32_e32 v70, v70
	v_exp_f32_e32 v71, v71
	s_nop 0
	v_add_f32_e32 v68, 1.0, v68
	v_add_f32_e32 v69, 1.0, v69
	v_add_f32_e32 v70, 1.0, v70
	v_add_f32_e32 v71, 1.0, v71
	v_rcp_f32_e32 v68, v68
	v_rcp_f32_e32 v69, v69
	v_rcp_f32_e32 v70, v70
	v_rcp_f32_e32 v71, v71
	s_nop 0
	v_mul_f32_e32 v64, v68, v64
	v_mul_f32_e32 v65, v69, v65
	v_mul_f32_e32 v66, v70, v66
	v_mul_f32_e32 v67, v71, v67
	v_mul_f32_e32 v136, v64, v136
	v_mul_f32_e32 v137, v65, v137
	v_mul_f32_e32 v138, v66, v138
	v_mul_f32_e32 v139, v67, v139
	v_cvt_pk_bf16_f32 v142, v136, v137
	v_cvt_pk_bf16_f32 v143, v138, v139
	global_store_dwordx4 v90, v[140:143], s[0:1]
	ds_read_b128 v[132:135], v82 offset:2048
	ds_read_b128 v[136:139], v82 offset:2064
	v_lshlrev_b32_e32 v64, 16, v104
	v_and_b32_e32 v65, 0xffff0000, v104
	v_lshlrev_b32_e32 v66, 16, v105
	v_and_b32_e32 v67, 0xffff0000, v105
	v_mul_f32_e32 v68, 0xbfb8aa3b, v64
	v_mul_f32_e32 v69, 0xbfb8aa3b, v65
	v_mul_f32_e32 v70, 0xbfb8aa3b, v66
	v_mul_f32_e32 v71, 0xbfb8aa3b, v67
	v_exp_f32_e32 v68, v68
	v_exp_f32_e32 v69, v69
	v_exp_f32_e32 v70, v70
	v_exp_f32_e32 v71, v71
	s_waitcnt lgkmcnt(0)
	v_add_f32_e32 v68, 1.0, v68
	v_add_f32_e32 v69, 1.0, v69
	v_add_f32_e32 v70, 1.0, v70
	v_add_f32_e32 v71, 1.0, v71
	v_rcp_f32_e32 v68, v68
	v_rcp_f32_e32 v69, v69
	v_rcp_f32_e32 v70, v70
	v_rcp_f32_e32 v71, v71
	s_nop 0
	v_mul_f32_e32 v64, v68, v64
	v_mul_f32_e32 v65, v69, v65
	v_mul_f32_e32 v66, v70, v66
	v_mul_f32_e32 v67, v71, v67
	v_mul_f32_e32 v132, v64, v132
	v_mul_f32_e32 v133, v65, v133
	v_mul_f32_e32 v134, v66, v134
	v_mul_f32_e32 v135, v67, v135
	v_cvt_pk_bf16_f32 v140, v132, v133
	v_cvt_pk_bf16_f32 v141, v134, v135
	v_lshlrev_b32_e32 v64, 16, v106
	v_and_b32_e32 v65, 0xffff0000, v106
	v_lshlrev_b32_e32 v66, 16, v107
	v_and_b32_e32 v67, 0xffff0000, v107
	v_mul_f32_e32 v68, 0xbfb8aa3b, v64
	v_mul_f32_e32 v69, 0xbfb8aa3b, v65
	v_mul_f32_e32 v70, 0xbfb8aa3b, v66
	v_mul_f32_e32 v71, 0xbfb8aa3b, v67
	v_exp_f32_e32 v68, v68
	v_exp_f32_e32 v69, v69
	v_exp_f32_e32 v70, v70
	v_exp_f32_e32 v71, v71
	s_nop 0
	v_add_f32_e32 v68, 1.0, v68
	v_add_f32_e32 v69, 1.0, v69
	v_add_f32_e32 v70, 1.0, v70
	v_add_f32_e32 v71, 1.0, v71
	v_rcp_f32_e32 v68, v68
	v_rcp_f32_e32 v69, v69
	v_rcp_f32_e32 v70, v70
	v_rcp_f32_e32 v71, v71
	s_nop 0
	v_mul_f32_e32 v64, v68, v64
	v_mul_f32_e32 v65, v69, v65
	v_mul_f32_e32 v66, v70, v66
	v_mul_f32_e32 v67, v71, v67
	v_mul_f32_e32 v136, v64, v136
	v_mul_f32_e32 v137, v65, v137
	v_mul_f32_e32 v138, v66, v138
	v_mul_f32_e32 v139, v67, v139
	v_cvt_pk_bf16_f32 v142, v136, v137
	v_cvt_pk_bf16_f32 v143, v138, v139
	global_store_dwordx4 v91, v[140:143], s[0:1]
	ds_read_b128 v[132:135], v82 offset:4096
	ds_read_b128 v[136:139], v82 offset:4112
	v_lshlrev_b32_e32 v64, 16, v108
	v_and_b32_e32 v65, 0xffff0000, v108
	v_lshlrev_b32_e32 v66, 16, v109
	v_and_b32_e32 v67, 0xffff0000, v109
	v_mul_f32_e32 v68, 0xbfb8aa3b, v64
	v_mul_f32_e32 v69, 0xbfb8aa3b, v65
	v_mul_f32_e32 v70, 0xbfb8aa3b, v66
	v_mul_f32_e32 v71, 0xbfb8aa3b, v67
	v_exp_f32_e32 v68, v68
	v_exp_f32_e32 v69, v69
	v_exp_f32_e32 v70, v70
	v_exp_f32_e32 v71, v71
	s_waitcnt lgkmcnt(0)
	v_add_f32_e32 v68, 1.0, v68
	v_add_f32_e32 v69, 1.0, v69
	v_add_f32_e32 v70, 1.0, v70
	v_add_f32_e32 v71, 1.0, v71
	v_rcp_f32_e32 v68, v68
	v_rcp_f32_e32 v69, v69
	v_rcp_f32_e32 v70, v70
	v_rcp_f32_e32 v71, v71
	s_nop 0
	v_mul_f32_e32 v64, v68, v64
	v_mul_f32_e32 v65, v69, v65
	v_mul_f32_e32 v66, v70, v66
	v_mul_f32_e32 v67, v71, v67
	v_mul_f32_e32 v132, v64, v132
	v_mul_f32_e32 v133, v65, v133
	v_mul_f32_e32 v134, v66, v134
	v_mul_f32_e32 v135, v67, v135
	v_cvt_pk_bf16_f32 v140, v132, v133
	v_cvt_pk_bf16_f32 v141, v134, v135
	v_lshlrev_b32_e32 v64, 16, v110
	v_and_b32_e32 v65, 0xffff0000, v110
	v_lshlrev_b32_e32 v66, 16, v111
	v_and_b32_e32 v67, 0xffff0000, v111
	v_mul_f32_e32 v68, 0xbfb8aa3b, v64
	v_mul_f32_e32 v69, 0xbfb8aa3b, v65
	v_mul_f32_e32 v70, 0xbfb8aa3b, v66
	v_mul_f32_e32 v71, 0xbfb8aa3b, v67
	v_exp_f32_e32 v68, v68
	v_exp_f32_e32 v69, v69
	v_exp_f32_e32 v70, v70
	v_exp_f32_e32 v71, v71
	s_nop 0
	v_add_f32_e32 v68, 1.0, v68
	v_add_f32_e32 v69, 1.0, v69
	v_add_f32_e32 v70, 1.0, v70
	v_add_f32_e32 v71, 1.0, v71
	v_rcp_f32_e32 v68, v68
	v_rcp_f32_e32 v69, v69
	v_rcp_f32_e32 v70, v70
	v_rcp_f32_e32 v71, v71
	s_nop 0
	v_mul_f32_e32 v64, v68, v64
	v_mul_f32_e32 v65, v69, v65
	v_mul_f32_e32 v66, v70, v66
	v_mul_f32_e32 v67, v71, v67
	v_mul_f32_e32 v136, v64, v136
	v_mul_f32_e32 v137, v65, v137
	v_mul_f32_e32 v138, v66, v138
	v_mul_f32_e32 v139, v67, v139
	v_cvt_pk_bf16_f32 v142, v136, v137
	v_cvt_pk_bf16_f32 v143, v138, v139
	global_store_dwordx4 v92, v[140:143], s[0:1]
	ds_read_b128 v[132:135], v82 offset:6144
	ds_read_b128 v[136:139], v82 offset:6160
	v_lshlrev_b32_e32 v64, 16, v112
	v_and_b32_e32 v65, 0xffff0000, v112
	v_lshlrev_b32_e32 v66, 16, v113
	v_and_b32_e32 v67, 0xffff0000, v113
	v_mul_f32_e32 v68, 0xbfb8aa3b, v64
	v_mul_f32_e32 v69, 0xbfb8aa3b, v65
	v_mul_f32_e32 v70, 0xbfb8aa3b, v66
	v_mul_f32_e32 v71, 0xbfb8aa3b, v67
	v_exp_f32_e32 v68, v68
	v_exp_f32_e32 v69, v69
	v_exp_f32_e32 v70, v70
	v_exp_f32_e32 v71, v71
	s_waitcnt lgkmcnt(0)
; __device__ __forceinline__ float bf2f(unsigned short b) { return __uint_as_float(((unsigned)b) << 16); }
; __device__ __forceinline__ unsigned short f2bf(float f) { return (unsigned short)(cvtpk(f, f) & 0xffffu); }
; __device__ __forceinline__ float siluf_(float x) { return x * sigmoidf_(x); }
; #define SBAR() __builtin_amdgcn_sched_barrier(0)
; __device__ __forceinline__ int crow(int r, int hi) { return (r & 3) + 8 * (r >> 2) + 4 * hi; }
; __device__ __forceinline__ void attn_body(const bf16_t* __restrict__ Qb, const bf16_t* __restrict__ Kh, const bf16_t* __restrict__ Vh,
;                                           bf16_t* __restrict__ Ob, const bf16_t* __restrict__ AGb, int seq, char* lds) {
;     ...
;   char* Ow = (char*)(Ob + (long)(wid * QBLK) * LDO); const char* Gw = (const char*)(AGb + (long)(wid * QBLK) * LDQ);
;   unsigned hv = hi, cv = r32;
;   asm volatile("" : "+v"(hv), "+v"(cv));
;   const unsigned gbase = (hv * 4u * LDQ + cv) * 2u, obase = (hv * 4u * LDO + cv) * 2u;
;   unsigned short gq[16][4];
; #pragma unroll
;   for (int r = 0; r < 16; ++r) { const int rc = (r & 3) + 8 * (r >> 2); const unsigned go = gbase + (unsigned)(rc * LDQ * 2);
; #pragma unroll
;     for (int d0 = 0; d0 < 4; ++d0) gq[r][d0] = *(const bf16_t*)(Gw + go + d0 * 64); }
;   SBAR();
; #pragma unroll
;   for (int r = 0; r < 16; ++r) { const int rc = (r & 3) + 8 * (r >> 2); const float rli = __builtin_amdgcn_rcpf(li_l[crow(r, hi)]);
;     const unsigned oo = obase + (unsigned)(rc * LDO * 2);
; #pragma unroll
;     for (int d0 = 0; d0 < 4; ++d0) *(bf16_t*)(Ow + oo + d0 * 64) = f2bf(o[d0][r] * rli * siluf_(bf2f(gq[r][d0]))); }
	v_add_f32_e32 v68, 1.0, v68
	v_add_f32_e32 v69, 1.0, v69
	v_add_f32_e32 v70, 1.0, v70
	v_add_f32_e32 v71, 1.0, v71
	v_rcp_f32_e32 v68, v68
	v_rcp_f32_e32 v69, v69
	v_rcp_f32_e32 v70, v70
	v_rcp_f32_e32 v71, v71
	s_nop 0
	v_mul_f32_e32 v64, v68, v64
	v_mul_f32_e32 v65, v69, v65
	v_mul_f32_e32 v66, v70, v66
	v_mul_f32_e32 v67, v71, v67
	v_mul_f32_e32 v132, v64, v132
	v_mul_f32_e32 v133, v65, v133
	v_mul_f32_e32 v134, v66, v134
	v_mul_f32_e32 v135, v67, v135
	v_cvt_pk_bf16_f32 v140, v132, v133
	v_cvt_pk_bf16_f32 v141, v134, v135
	v_lshlrev_b32_e32 v64, 16, v114
	v_and_b32_e32 v65, 0xffff0000, v114
	v_lshlrev_b32_e32 v66, 16, v115
	v_and_b32_e32 v67, 0xffff0000, v115
	v_mul_f32_e32 v68, 0xbfb8aa3b, v64
	v_mul_f32_e32 v69, 0xbfb8aa3b, v65
	v_mul_f32_e32 v70, 0xbfb8aa3b, v66
	v_mul_f32_e32 v71, 0xbfb8aa3b, v67
	v_exp_f32_e32 v68, v68
	v_exp_f32_e32 v69, v69
	v_exp_f32_e32 v70, v70
	v_exp_f32_e32 v71, v71
	s_nop 0
	v_add_f32_e32 v68, 1.0, v68
	v_add_f32_e32 v69, 1.0, v69
	v_add_f32_e32 v70, 1.0, v70
	v_add_f32_e32 v71, 1.0, v71
	v_rcp_f32_e32 v68, v68
	v_rcp_f32_e32 v69, v69
	v_rcp_f32_e32 v70, v70
	v_rcp_f32_e32 v71, v71
	s_nop 0
	v_mul_f32_e32 v64, v68, v64
	v_mul_f32_e32 v65, v69, v65
	v_mul_f32_e32 v66, v70, v66
	v_mul_f32_e32 v67, v71, v67
	v_mul_f32_e32 v136, v64, v136
	v_mul_f32_e32 v137, v65, v137
	v_mul_f32_e32 v138, v66, v138
	v_mul_f32_e32 v139, v67, v139
	v_cvt_pk_bf16_f32 v142, v136, v137
	v_cvt_pk_bf16_f32 v143, v138, v139
	global_store_dwordx4 v93, v[140:143], s[0:1]
	s_waitcnt lgkmcnt(0)
	ds_write_b32 v81, v32
	ds_write_b32 v81, v33 offset:256
	ds_write_b32 v81, v34 offset:512
	ds_write_b32 v81, v35 offset:768
	ds_write_b32 v81, v36 offset:2048
	ds_write_b32 v81, v37 offset:2304
	ds_write_b32 v81, v38 offset:2560
	ds_write_b32 v81, v39 offset:2816
	ds_write_b32 v81, v40 offset:4096
	ds_write_b32 v81, v41 offset:4352
	ds_write_b32 v81, v42 offset:4608
	ds_write_b32 v81, v43 offset:4864
	ds_write_b32 v81, v44 offset:6144
	ds_write_b32 v81, v45 offset:6400
	ds_write_b32 v81, v46 offset:6656
	ds_write_b32 v81, v47 offset:6912
	ds_write_b32 v81, v16 offset:128
	ds_write_b32 v81, v17 offset:384
	ds_write_b32 v81, v18 offset:640
	ds_write_b32 v81, v19 offset:896
	ds_write_b32 v81, v20 offset:2176
	ds_write_b32 v81, v21 offset:2432
	ds_write_b32 v81, v22 offset:2688
	ds_write_b32 v81, v23 offset:2944
	ds_write_b32 v81, v24 offset:4224
	ds_write_b32 v81, v25 offset:4480
	ds_write_b32 v81, v26 offset:4736
	ds_write_b32 v81, v27 offset:4992
	ds_write_b32 v81, v28 offset:6272
	ds_write_b32 v81, v29 offset:6528
	ds_write_b32 v81, v30 offset:6784
	ds_write_b32 v81, v31 offset:7040
	s_waitcnt lgkmcnt(0)
	ds_read_b128 v[132:135], v82
	ds_read_b128 v[136:139], v82 offset:16
	v_lshlrev_b32_e32 v64, 16, v116
	v_and_b32_e32 v65, 0xffff0000, v116
	v_lshlrev_b32_e32 v66, 16, v117
	v_and_b32_e32 v67, 0xffff0000, v117
	v_mul_f32_e32 v68, 0xbfb8aa3b, v64
	v_mul_f32_e32 v69, 0xbfb8aa3b, v65
	v_mul_f32_e32 v70, 0xbfb8aa3b, v66
	v_mul_f32_e32 v71, 0xbfb8aa3b, v67
	v_exp_f32_e32 v68, v68
	v_exp_f32_e32 v69, v69
	v_exp_f32_e32 v70, v70
	v_exp_f32_e32 v71, v71
	s_waitcnt lgkmcnt(0)
	v_add_f32_e32 v68, 1.0, v68
	v_add_f32_e32 v69, 1.0, v69
	v_add_f32_e32 v70, 1.0, v70
	v_add_f32_e32 v71, 1.0, v71
	v_rcp_f32_e32 v68, v68
	v_rcp_f32_e32 v69, v69
	v_rcp_f32_e32 v70, v70
	v_rcp_f32_e32 v71, v71
	s_nop 0
	v_mul_f32_e32 v64, v68, v64
	v_mul_f32_e32 v65, v69, v65
	v_mul_f32_e32 v66, v70, v66
	v_mul_f32_e32 v67, v71, v67
	v_mul_f32_e32 v132, v64, v132
	v_mul_f32_e32 v133, v65, v133
	v_mul_f32_e32 v134, v66, v134
	v_mul_f32_e32 v135, v67, v135
	v_cvt_pk_bf16_f32 v140, v132, v133
	v_cvt_pk_bf16_f32 v141, v134, v135
	v_lshlrev_b32_e32 v64, 16, v118
	v_and_b32_e32 v65, 0xffff0000, v118
	v_lshlrev_b32_e32 v66, 16, v119
	v_and_b32_e32 v67, 0xffff0000, v119
	v_mul_f32_e32 v68, 0xbfb8aa3b, v64
	v_mul_f32_e32 v69, 0xbfb8aa3b, v65
	v_mul_f32_e32 v70, 0xbfb8aa3b, v66
	v_mul_f32_e32 v71, 0xbfb8aa3b, v67
	v_exp_f32_e32 v68, v68
	v_exp_f32_e32 v69, v69
	v_exp_f32_e32 v70, v70
	v_exp_f32_e32 v71, v71
	s_nop 0
	v_add_f32_e32 v68, 1.0, v68
	v_add_f32_e32 v69, 1.0, v69
	v_add_f32_e32 v70, 1.0, v70
	v_add_f32_e32 v71, 1.0, v71
	v_rcp_f32_e32 v68, v68
	v_rcp_f32_e32 v69, v69
	v_rcp_f32_e32 v70, v70
	v_rcp_f32_e32 v71, v71
	s_nop 0
	v_mul_f32_e32 v64, v68, v64
	v_mul_f32_e32 v65, v69, v65
	v_mul_f32_e32 v66, v70, v66
	v_mul_f32_e32 v67, v71, v67
	v_mul_f32_e32 v136, v64, v136
	v_mul_f32_e32 v137, v65, v137
	v_mul_f32_e32 v138, v66, v138
	v_mul_f32_e32 v139, v67, v139
	v_cvt_pk_bf16_f32 v142, v136, v137
	v_cvt_pk_bf16_f32 v143, v138, v139
	global_store_dwordx4 v90, v[140:143], s[0:1] offset:128
	ds_read_b128 v[132:135], v82 offset:2048
	ds_read_b128 v[136:139], v82 offset:2064
	v_lshlrev_b32_e32 v64, 16, v120
	v_and_b32_e32 v65, 0xffff0000, v120
	v_lshlrev_b32_e32 v66, 16, v121
	v_and_b32_e32 v67, 0xffff0000, v121
	v_mul_f32_e32 v68, 0xbfb8aa3b, v64
	v_mul_f32_e32 v69, 0xbfb8aa3b, v65
	v_mul_f32_e32 v70, 0xbfb8aa3b, v66
	v_mul_f32_e32 v71, 0xbfb8aa3b, v67
	v_exp_f32_e32 v68, v68
	v_exp_f32_e32 v69, v69
	v_exp_f32_e32 v70, v70
	v_exp_f32_e32 v71, v71
	s_waitcnt lgkmcnt(0)
; __device__ __forceinline__ float bf2f(unsigned short b) { return __uint_as_float(((unsigned)b) << 16); }
; __device__ __forceinline__ unsigned short f2bf(float f) { return (unsigned short)(cvtpk(f, f) & 0xffffu); }
; __device__ __forceinline__ float siluf_(float x) { return x * sigmoidf_(x); }
; #define SBAR() __builtin_amdgcn_sched_barrier(0)
; __device__ __forceinline__ int crow(int r, int hi) { return (r & 3) + 8 * (r >> 2) + 4 * hi; }
; __device__ __forceinline__ void attn_body(const bf16_t* __restrict__ Qb, const bf16_t* __restrict__ Kh, const bf16_t* __restrict__ Vh,
;                                           bf16_t* __restrict__ Ob, const bf16_t* __restrict__ AGb, int seq, char* lds) {
;     ...
;   char* Ow = (char*)(Ob + (long)(wid * QBLK) * LDO); const char* Gw = (const char*)(AGb + (long)(wid * QBLK) * LDQ);
;   unsigned hv = hi, cv = r32;
;   asm volatile("" : "+v"(hv), "+v"(cv));
;   const unsigned gbase = (hv * 4u * LDQ + cv) * 2u, obase = (hv * 4u * LDO + cv) * 2u;
;   unsigned short gq[16][4];
; #pragma unroll
;   for (int r = 0; r < 16; ++r) { const int rc = (r & 3) + 8 * (r >> 2); const unsigned go = gbase + (unsigned)(rc * LDQ * 2);
; #pragma unroll
;     for (int d0 = 0; d0 < 4; ++d0) gq[r][d0] = *(const bf16_t*)(Gw + go + d0 * 64); }
;   SBAR();
; #pragma unroll
;   for (int r = 0; r < 16; ++r) { const int rc = (r & 3) + 8 * (r >> 2); const float rli = __builtin_amdgcn_rcpf(li_l[crow(r, hi)]);
;     const unsigned oo = obase + (unsigned)(rc * LDO * 2);
; #pragma unroll
;     for (int d0 = 0; d0 < 4; ++d0) *(bf16_t*)(Ow + oo + d0 * 64) = f2bf(o[d0][r] * rli * siluf_(bf2f(gq[r][d0]))); }
	v_add_f32_e32 v68, 1.0, v68
	v_add_f32_e32 v69, 1.0, v69
	v_add_f32_e32 v70, 1.0, v70
	v_add_f32_e32 v71, 1.0, v71
	v_rcp_f32_e32 v68, v68
	v_rcp_f32_e32 v69, v69
	v_rcp_f32_e32 v70, v70
	v_rcp_f32_e32 v71, v71
	s_nop 0
	v_mul_f32_e32 v64, v68, v64
	v_mul_f32_e32 v65, v69, v65
	v_mul_f32_e32 v66, v70, v66
	v_mul_f32_e32 v67, v71, v67
	v_mul_f32_e32 v132, v64, v132
	v_mul_f32_e32 v133, v65, v133
	v_mul_f32_e32 v134, v66, v134
	v_mul_f32_e32 v135, v67, v135
	v_cvt_pk_bf16_f32 v140, v132, v133
	v_cvt_pk_bf16_f32 v141, v134, v135
	v_lshlrev_b32_e32 v64, 16, v122
	v_and_b32_e32 v65, 0xffff0000, v122
	v_lshlrev_b32_e32 v66, 16, v123
	v_and_b32_e32 v67, 0xffff0000, v123
	v_mul_f32_e32 v68, 0xbfb8aa3b, v64
	v_mul_f32_e32 v69, 0xbfb8aa3b, v65
	v_mul_f32_e32 v70, 0xbfb8aa3b, v66
	v_mul_f32_e32 v71, 0xbfb8aa3b, v67
	v_exp_f32_e32 v68, v68
	v_exp_f32_e32 v69, v69
	v_exp_f32_e32 v70, v70
	v_exp_f32_e32 v71, v71
	s_nop 0
	v_add_f32_e32 v68, 1.0, v68
	v_add_f32_e32 v69, 1.0, v69
	v_add_f32_e32 v70, 1.0, v70
	v_add_f32_e32 v71, 1.0, v71
	v_rcp_f32_e32 v68, v68
	v_rcp_f32_e32 v69, v69
	v_rcp_f32_e32 v70, v70
	v_rcp_f32_e32 v71, v71
	s_nop 0
	v_mul_f32_e32 v64, v68, v64
	v_mul_f32_e32 v65, v69, v65
	v_mul_f32_e32 v66, v70, v66
	v_mul_f32_e32 v67, v71, v67
	v_mul_f32_e32 v136, v64, v136
	v_mul_f32_e32 v137, v65, v137
	v_mul_f32_e32 v138, v66, v138
	v_mul_f32_e32 v139, v67, v139
	v_cvt_pk_bf16_f32 v142, v136, v137
	v_cvt_pk_bf16_f32 v143, v138, v139
	global_store_dwordx4 v91, v[140:143], s[0:1] offset:128
	ds_read_b128 v[132:135], v82 offset:4096
	ds_read_b128 v[136:139], v82 offset:4112
	v_lshlrev_b32_e32 v64, 16, v124
	v_and_b32_e32 v65, 0xffff0000, v124
	v_lshlrev_b32_e32 v66, 16, v125
	v_and_b32_e32 v67, 0xffff0000, v125
	v_mul_f32_e32 v68, 0xbfb8aa3b, v64
	v_mul_f32_e32 v69, 0xbfb8aa3b, v65
	v_mul_f32_e32 v70, 0xbfb8aa3b, v66
	v_mul_f32_e32 v71, 0xbfb8aa3b, v67
	v_exp_f32_e32 v68, v68
	v_exp_f32_e32 v69, v69
	v_exp_f32_e32 v70, v70
	v_exp_f32_e32 v71, v71
	s_waitcnt lgkmcnt(0)
	v_add_f32_e32 v68, 1.0, v68
	v_add_f32_e32 v69, 1.0, v69
	v_add_f32_e32 v70, 1.0, v70
	v_add_f32_e32 v71, 1.0, v71
	v_rcp_f32_e32 v68, v68
	v_rcp_f32_e32 v69, v69
	v_rcp_f32_e32 v70, v70
	v_rcp_f32_e32 v71, v71
	s_nop 0
	v_mul_f32_e32 v64, v68, v64
	v_mul_f32_e32 v65, v69, v65
	v_mul_f32_e32 v66, v70, v66
	v_mul_f32_e32 v67, v71, v67
	v_mul_f32_e32 v132, v64, v132
	v_mul_f32_e32 v133, v65, v133
	v_mul_f32_e32 v134, v66, v134
	v_mul_f32_e32 v135, v67, v135
	v_cvt_pk_bf16_f32 v140, v132, v133
	v_cvt_pk_bf16_f32 v141, v134, v135
	v_lshlrev_b32_e32 v64, 16, v126
	v_and_b32_e32 v65, 0xffff0000, v126
	v_lshlrev_b32_e32 v66, 16, v127
	v_and_b32_e32 v67, 0xffff0000, v127
	v_mul_f32_e32 v68, 0xbfb8aa3b, v64
	v_mul_f32_e32 v69, 0xbfb8aa3b, v65
	v_mul_f32_e32 v70, 0xbfb8aa3b, v66
	v_mul_f32_e32 v71, 0xbfb8aa3b, v67
	v_exp_f32_e32 v68, v68
	v_exp_f32_e32 v69, v69
	v_exp_f32_e32 v70, v70
	v_exp_f32_e32 v71, v71
	s_nop 0
	v_add_f32_e32 v68, 1.0, v68
	v_add_f32_e32 v69, 1.0, v69
	v_add_f32_e32 v70, 1.0, v70
	v_add_f32_e32 v71, 1.0, v71
	v_rcp_f32_e32 v68, v68
	v_rcp_f32_e32 v69, v69
	v_rcp_f32_e32 v70, v70
	v_rcp_f32_e32 v71, v71
	s_nop 0
	v_mul_f32_e32 v64, v68, v64
	v_mul_f32_e32 v65, v69, v65
	v_mul_f32_e32 v66, v70, v66
	v_mul_f32_e32 v67, v71, v67
	v_mul_f32_e32 v136, v64, v136
	v_mul_f32_e32 v137, v65, v137
	v_mul_f32_e32 v138, v66, v138
	v_mul_f32_e32 v139, v67, v139
	v_cvt_pk_bf16_f32 v142, v136, v137
	v_cvt_pk_bf16_f32 v143, v138, v139
	global_store_dwordx4 v92, v[140:143], s[0:1] offset:128
	ds_read_b128 v[132:135], v82 offset:6144
	ds_read_b128 v[136:139], v82 offset:6160
	v_lshlrev_b32_e32 v64, 16, v128
	v_and_b32_e32 v65, 0xffff0000, v128
	v_lshlrev_b32_e32 v66, 16, v129
	v_and_b32_e32 v67, 0xffff0000, v129
	v_mul_f32_e32 v68, 0xbfb8aa3b, v64
	v_mul_f32_e32 v69, 0xbfb8aa3b, v65
	v_mul_f32_e32 v70, 0xbfb8aa3b, v66
	v_mul_f32_e32 v71, 0xbfb8aa3b, v67
	v_exp_f32_e32 v68, v68
	v_exp_f32_e32 v69, v69
	v_exp_f32_e32 v70, v70
	v_exp_f32_e32 v71, v71
	s_waitcnt lgkmcnt(0)
	v_add_f32_e32 v68, 1.0, v68
	v_add_f32_e32 v69, 1.0, v69
	v_add_f32_e32 v70, 1.0, v70
	v_add_f32_e32 v71, 1.0, v71
	v_rcp_f32_e32 v68, v68
	v_rcp_f32_e32 v69, v69
	v_rcp_f32_e32 v70, v70
	v_rcp_f32_e32 v71, v71
	s_nop 0
	v_mul_f32_e32 v64, v68, v64
	v_mul_f32_e32 v65, v69, v65
	v_mul_f32_e32 v66, v70, v66
	v_mul_f32_e32 v67, v71, v67
	v_mul_f32_e32 v132, v64, v132
	v_mul_f32_e32 v133, v65, v133
	v_mul_f32_e32 v134, v66, v134
	v_mul_f32_e32 v135, v67, v135
	v_cvt_pk_bf16_f32 v140, v132, v133
	v_cvt_pk_bf16_f32 v141, v134, v135
	v_lshlrev_b32_e32 v64, 16, v130
	v_and_b32_e32 v65, 0xffff0000, v130
	v_lshlrev_b32_e32 v66, 16, v131
	v_and_b32_e32 v67, 0xffff0000, v131
	v_mul_f32_e32 v68, 0xbfb8aa3b, v64
	v_mul_f32_e32 v69, 0xbfb8aa3b, v65
	v_mul_f32_e32 v70, 0xbfb8aa3b, v66
	v_mul_f32_e32 v71, 0xbfb8aa3b, v67
	v_exp_f32_e32 v68, v68
	v_exp_f32_e32 v69, v69
	v_exp_f32_e32 v70, v70
	v_exp_f32_e32 v71, v71
	s_nop 0
	v_add_f32_e32 v68, 1.0, v68
	v_add_f32_e32 v69, 1.0, v69
	v_add_f32_e32 v70, 1.0, v70
	v_add_f32_e32 v71, 1.0, v71
	v_rcp_f32_e32 v68, v68
	v_rcp_f32_e32 v69, v69
	v_rcp_f32_e32 v70, v70
	v_rcp_f32_e32 v71, v71
	s_nop 0
	v_mul_f32_e32 v64, v68, v64
	v_mul_f32_e32 v65, v69, v65
	v_mul_f32_e32 v66, v70, v66
	v_mul_f32_e32 v67, v71, v67
	v_mul_f32_e32 v136, v64, v136
	v_mul_f32_e32 v137, v65, v137
	v_mul_f32_e32 v138, v66, v138
	v_mul_f32_e32 v139, v67, v139
	v_cvt_pk_bf16_f32 v142, v136, v137
	v_cvt_pk_bf16_f32 v143, v138, v139
	global_store_dwordx4 v93, v[140:143], s[0:1] offset:128
	s_add_i32 s15, s15, s88
	v_readlane_b32 s0, v245, 41
	s_cmp_lt_i32 s15, s0
	s_waitcnt lgkmcnt(0)
	s_barrier
	s_cbranch_scc0 .LBB0_185
